# v28
# speedup vs baseline: 1.0237x; 1.0057x over previous
.LBB0_219:
	ds_read_b128 v[164:167], v160
	ds_read_b128 v[168:171], v160 offset:1024
	ds_read_b128 v[172:175], v160 offset:2048
	ds_read_b128 v[176:179], v160 offset:3072
	v_lshl_add_u64 v[240:241], v[144:145], 0, s[6:7]
	s_add_i32 m0, s100, 0xbf80
	ds_read_b128 v[184:187], v152
	ds_read_b128 v[190:193], v152 offset:1024
	ds_read_b128 v[194:197], v151
	ds_read_b128 v[198:201], v151 offset:1024
	ds_read_b128 v[206:209], v150
	ds_read_b128 v[212:215], v150 offset:1024
	ds_read_b128 v[216:219], v149
	ds_read_b128 v[220:223], v149 offset:1024
	global_load_lds_dwordx4 v[240:241], off offset:128
	s_add_i32 m0, s100, 0xdf80
	v_lshl_add_u64 v[242:243], v[142:143], 0, s[6:7]
	global_load_lds_dwordx4 v[242:243], off offset:128
	s_waitcnt lgkmcnt(8)
	s_barrier
	s_waitcnt lgkmcnt(0)
	s_setprio 1
	v_mfma_f32_16x16x32_bf16 v[124:127], v[184:187], v[164:167], v[124:127]
	v_mfma_f32_16x16x32_bf16 v[120:123], v[184:187], v[172:175], v[120:123]
	v_mfma_f32_16x16x32_bf16 v[116:119], v[194:197], v[164:167], v[116:119]
	v_mfma_f32_16x16x32_bf16 v[112:115], v[194:197], v[172:175], v[112:115]
	v_mfma_f32_16x16x32_bf16 v[108:111], v[206:209], v[164:167], v[108:111]
	v_mfma_f32_16x16x32_bf16 v[104:107], v[206:209], v[172:175], v[104:107]
	v_mfma_f32_16x16x32_bf16 v[100:103], v[216:219], v[164:167], v[100:103]
	v_mfma_f32_16x16x32_bf16 v[96:99], v[216:219], v[172:175], v[96:99]
	v_mfma_f32_16x16x32_bf16 v[124:127], v[190:193], v[168:171], v[124:127]
	v_mfma_f32_16x16x32_bf16 v[120:123], v[190:193], v[176:179], v[120:123]
	v_mfma_f32_16x16x32_bf16 v[116:119], v[198:201], v[168:171], v[116:119]
	v_mfma_f32_16x16x32_bf16 v[112:115], v[198:201], v[176:179], v[112:115]
	v_mfma_f32_16x16x32_bf16 v[108:111], v[212:215], v[168:171], v[108:111]
	v_mfma_f32_16x16x32_bf16 v[104:107], v[212:215], v[176:179], v[104:107]
	v_mfma_f32_16x16x32_bf16 v[100:103], v[220:223], v[168:171], v[100:103]
	v_mfma_f32_16x16x32_bf16 v[96:99], v[220:223], v[176:179], v[96:99]
	s_setprio 0
	s_barrier
	v_lshl_add_u64 v[244:245], v[130:131], 0, s[6:7]
	s_add_i32 m0, s101, 0xff00
	ds_read_b128 v[224:227], v159
	ds_read_b128 v[228:231], v159 offset:1024
	ds_read_b128 v[232:235], v159 offset:2048
	ds_read_b128 v[236:239], v159 offset:3072
	global_load_lds_dwordx4 v[244:245], off offset:256
	v_lshl_add_u64 v[246:247], v[132:133], 0, s[6:7]
	s_add_i32 m0, m0, 0x2000
	s_add_i32 s11, s11, 2
	global_load_lds_dwordx4 v[246:247], off offset:256
	s_barrier
	s_waitcnt lgkmcnt(0)
	s_setprio 1
	v_mfma_f32_16x16x32_bf16 v[92:95], v[184:187], v[224:227], v[92:95]
	v_mfma_f32_16x16x32_bf16 v[88:91], v[184:187], v[232:235], v[88:91]
	v_mfma_f32_16x16x32_bf16 v[84:87], v[194:197], v[224:227], v[84:87]
	v_mfma_f32_16x16x32_bf16 v[80:83], v[194:197], v[232:235], v[80:83]
	v_mfma_f32_16x16x32_bf16 v[76:79], v[206:209], v[224:227], v[76:79]
	v_mfma_f32_16x16x32_bf16 v[72:75], v[206:209], v[232:235], v[72:75]
	v_mfma_f32_16x16x32_bf16 v[68:71], v[216:219], v[224:227], v[68:71]
	v_mfma_f32_16x16x32_bf16 v[64:67], v[216:219], v[232:235], v[64:67]
	v_mfma_f32_16x16x32_bf16 v[92:95], v[190:193], v[228:231], v[92:95]
	v_mfma_f32_16x16x32_bf16 v[88:91], v[190:193], v[236:239], v[88:91]
	v_mfma_f32_16x16x32_bf16 v[84:87], v[198:201], v[228:231], v[84:87]
	v_mfma_f32_16x16x32_bf16 v[80:83], v[198:201], v[236:239], v[80:83]
	v_mfma_f32_16x16x32_bf16 v[76:79], v[212:215], v[228:231], v[76:79]
	v_mfma_f32_16x16x32_bf16 v[72:75], v[212:215], v[236:239], v[72:75]
	v_mfma_f32_16x16x32_bf16 v[68:71], v[220:223], v[228:231], v[68:71]
	v_mfma_f32_16x16x32_bf16 v[64:67], v[220:223], v[236:239], v[64:67]
	s_setprio 0
	v_lshl_add_u64 v[248:249], v[134:135], 0, s[6:7]
	v_lshl_add_u64 v[250:251], v[248:249], 0, s[64:65]
	s_mov_b32 m0, s100
	s_barrier
	ds_read_b128 v[184:187], v152 offset:16384
	ds_read_b128 v[190:193], v152 offset:17408
	ds_read_b128 v[194:197], v151 offset:16384
	ds_read_b128 v[198:201], v151 offset:17408
	ds_read_b128 v[206:209], v150 offset:16384
	ds_read_b128 v[212:215], v150 offset:17408
	ds_read_b128 v[216:219], v149 offset:16384
	ds_read_b128 v[220:223], v149 offset:17408
	global_load_lds_dwordx4 v[250:251], off
	s_add_i32 m0, s100, 0x1f00
	v_lshl_add_u64 v[250:251], v[136:137], 0, s[6:7]
	global_load_lds_dwordx4 v[250:251], off offset:256
	s_barrier
	s_waitcnt lgkmcnt(0)
	s_setprio 1
	v_mfma_f32_16x16x32_bf16 v[60:63], v[184:187], v[164:167], v[60:63]
	v_mfma_f32_16x16x32_bf16 v[56:59], v[184:187], v[172:175], v[56:59]
	v_mfma_f32_16x16x32_bf16 v[52:55], v[194:197], v[164:167], v[52:55]
	v_mfma_f32_16x16x32_bf16 v[48:51], v[194:197], v[172:175], v[48:51]
	v_mfma_f32_16x16x32_bf16 v[44:47], v[206:209], v[164:167], v[44:47]
	v_mfma_f32_16x16x32_bf16 v[40:43], v[206:209], v[172:175], v[40:43]
	v_mfma_f32_16x16x32_bf16 v[36:39], v[216:219], v[164:167], v[36:39]
	v_mfma_f32_16x16x32_bf16 v[32:35], v[216:219], v[172:175], v[32:35]
	v_mfma_f32_16x16x32_bf16 v[60:63], v[190:193], v[168:171], v[60:63]
	v_mfma_f32_16x16x32_bf16 v[56:59], v[190:193], v[176:179], v[56:59]
	v_mfma_f32_16x16x32_bf16 v[52:55], v[198:201], v[168:171], v[52:55]
	v_mfma_f32_16x16x32_bf16 v[48:51], v[198:201], v[176:179], v[48:51]
	v_mfma_f32_16x16x32_bf16 v[44:47], v[212:215], v[168:171], v[44:47]
	v_mfma_f32_16x16x32_bf16 v[40:43], v[212:215], v[176:179], v[40:43]
	v_mfma_f32_16x16x32_bf16 v[36:39], v[220:223], v[168:171], v[36:39]
	v_mfma_f32_16x16x32_bf16 v[32:35], v[220:223], v[176:179], v[32:35]
	s_setprio 0
	s_barrier
	v_lshl_add_u64 v[252:253], v[140:141], 0, s[6:7]
	s_add_i32 m0, s101, 0x13f00
	global_load_lds_dwordx4 v[252:253], off offset:256
	s_add_i32 m0, m0, 0x2000
	v_lshl_add_u64 v[188:189], v[138:139], 0, s[6:7]
	global_load_lds_dwordx4 v[188:189], off offset:256
	s_waitcnt vmcnt(6)
	s_barrier
	s_setprio 1
	v_mfma_f32_16x16x32_bf16 v[28:31], v[184:187], v[224:227], v[28:31]
	v_mfma_f32_16x16x32_bf16 v[24:27], v[184:187], v[232:235], v[24:27]
	v_mfma_f32_16x16x32_bf16 v[20:23], v[194:197], v[224:227], v[20:23]
	v_mfma_f32_16x16x32_bf16 v[16:19], v[194:197], v[232:235], v[16:19]
	v_mfma_f32_16x16x32_bf16 v[12:15], v[206:209], v[224:227], v[12:15]
	v_mfma_f32_16x16x32_bf16 v[8:11], v[206:209], v[232:235], v[8:11]
	v_mfma_f32_16x16x32_bf16 v[4:7], v[216:219], v[224:227], v[4:7]
	v_mfma_f32_16x16x32_bf16 v[0:3], v[216:219], v[232:235], v[0:3]
	v_mfma_f32_16x16x32_bf16 v[28:31], v[190:193], v[228:231], v[28:31]
	v_mfma_f32_16x16x32_bf16 v[24:27], v[190:193], v[236:239], v[24:27]
	v_mfma_f32_16x16x32_bf16 v[20:23], v[198:201], v[228:231], v[20:23]
	v_mfma_f32_16x16x32_bf16 v[16:19], v[198:201], v[236:239], v[16:19]
	v_mfma_f32_16x16x32_bf16 v[12:15], v[212:215], v[228:231], v[12:15]
	v_mfma_f32_16x16x32_bf16 v[8:11], v[212:215], v[236:239], v[8:11]
	v_mfma_f32_16x16x32_bf16 v[4:7], v[220:223], v[228:231], v[4:7]
	v_mfma_f32_16x16x32_bf16 v[0:3], v[220:223], v[236:239], v[0:3]
	s_setprio 0
	s_barrier
	ds_read_b128 v[164:167], v155
	ds_read_b128 v[168:171], v155 offset:1024
	ds_read_b128 v[172:175], v155 offset:2048
	ds_read_b128 v[176:179], v155 offset:3072
	s_add_i32 m0, s100, 0x3f00
	ds_read_b128 v[184:187], v152 offset:32768
	ds_read_b128 v[190:193], v152 offset:33792
	ds_read_b128 v[194:197], v151 offset:32768
	ds_read_b128 v[198:201], v151 offset:33792
	ds_read_b128 v[206:209], v150 offset:32768
	ds_read_b128 v[212:215], v150 offset:33792
	ds_read_b128 v[216:219], v149 offset:32768
	global_load_lds_dwordx4 v[240:241], off offset:256
	s_add_i32 m0, s100, 0x5f00
	ds_read_b128 v[220:223], v149 offset:33792
	global_load_lds_dwordx4 v[242:243], off offset:256
	s_waitcnt lgkmcnt(8)
	s_barrier
	s_waitcnt lgkmcnt(0)
	s_setprio 1
	v_mfma_f32_16x16x32_bf16 v[124:127], v[184:187], v[164:167], v[124:127]
	v_mfma_f32_16x16x32_bf16 v[120:123], v[184:187], v[172:175], v[120:123]
	v_mfma_f32_16x16x32_bf16 v[116:119], v[194:197], v[164:167], v[116:119]
	v_mfma_f32_16x16x32_bf16 v[112:115], v[194:197], v[172:175], v[112:115]
	v_mfma_f32_16x16x32_bf16 v[108:111], v[206:209], v[164:167], v[108:111]
	v_mfma_f32_16x16x32_bf16 v[104:107], v[206:209], v[172:175], v[104:107]
	v_mfma_f32_16x16x32_bf16 v[100:103], v[216:219], v[164:167], v[100:103]
	v_mfma_f32_16x16x32_bf16 v[96:99], v[216:219], v[172:175], v[96:99]
	v_mfma_f32_16x16x32_bf16 v[124:127], v[190:193], v[168:171], v[124:127]
	v_mfma_f32_16x16x32_bf16 v[120:123], v[190:193], v[176:179], v[120:123]
	v_mfma_f32_16x16x32_bf16 v[116:119], v[198:201], v[168:171], v[116:119]
	v_mfma_f32_16x16x32_bf16 v[112:115], v[198:201], v[176:179], v[112:115]
	v_mfma_f32_16x16x32_bf16 v[108:111], v[212:215], v[168:171], v[108:111]
	v_mfma_f32_16x16x32_bf16 v[104:107], v[212:215], v[176:179], v[104:107]
	v_mfma_f32_16x16x32_bf16 v[100:103], v[220:223], v[168:171], v[100:103]
	v_mfma_f32_16x16x32_bf16 v[96:99], v[220:223], v[176:179], v[96:99]
	s_setprio 0
	s_barrier
	s_add_i32 m0, s101, 0x17e80
	ds_read_b128 v[224:227], v153
	ds_read_b128 v[228:231], v153 offset:1024
	ds_read_b128 v[232:235], v153 offset:2048
	global_load_lds_dwordx4 v[244:245], off offset:384
	s_add_i32 m0, m0, 0x2000
	ds_read_b128 v[236:239], v153 offset:3072
	global_load_lds_dwordx4 v[246:247], off offset:384
	s_barrier
	s_waitcnt lgkmcnt(0)
	s_setprio 1
	v_mfma_f32_16x16x32_bf16 v[92:95], v[184:187], v[224:227], v[92:95]
	v_mfma_f32_16x16x32_bf16 v[88:91], v[184:187], v[232:235], v[88:91]
	v_mfma_f32_16x16x32_bf16 v[84:87], v[194:197], v[224:227], v[84:87]
	v_mfma_f32_16x16x32_bf16 v[80:83], v[194:197], v[232:235], v[80:83]
	v_mfma_f32_16x16x32_bf16 v[76:79], v[206:209], v[224:227], v[76:79]
	v_mfma_f32_16x16x32_bf16 v[72:75], v[206:209], v[232:235], v[72:75]
	v_mfma_f32_16x16x32_bf16 v[68:71], v[216:219], v[224:227], v[68:71]
	v_mfma_f32_16x16x32_bf16 v[64:67], v[216:219], v[232:235], v[64:67]
	v_mfma_f32_16x16x32_bf16 v[92:95], v[190:193], v[228:231], v[92:95]
	v_mfma_f32_16x16x32_bf16 v[88:91], v[190:193], v[236:239], v[88:91]
	v_mfma_f32_16x16x32_bf16 v[84:87], v[198:201], v[228:231], v[84:87]
	v_mfma_f32_16x16x32_bf16 v[80:83], v[198:201], v[236:239], v[80:83]
	v_mfma_f32_16x16x32_bf16 v[76:79], v[212:215], v[228:231], v[76:79]
	v_mfma_f32_16x16x32_bf16 v[72:75], v[212:215], v[236:239], v[72:75]
	v_mfma_f32_16x16x32_bf16 v[68:71], v[220:223], v[228:231], v[68:71]
	v_mfma_f32_16x16x32_bf16 v[64:67], v[220:223], v[236:239], v[64:67]
	s_setprio 0
	s_add_i32 m0, s100, 0x7e80
	s_barrier
	ds_read_b128 v[184:187], v152 offset:49152
	ds_read_b128 v[190:193], v152 offset:50176
	ds_read_b128 v[194:197], v151 offset:49152
	ds_read_b128 v[198:201], v151 offset:50176
	ds_read_b128 v[206:209], v150 offset:49152
	ds_read_b128 v[212:215], v150 offset:50176
	ds_read_b128 v[216:219], v149 offset:49152
	global_load_lds_dwordx4 v[248:249], off offset:384
	s_add_i32 m0, s100, 0x9e80
	ds_read_b128 v[220:223], v149 offset:50176
	global_load_lds_dwordx4 v[250:251], off offset:384
	s_barrier
	s_waitcnt lgkmcnt(0)
	s_setprio 1
	v_mfma_f32_16x16x32_bf16 v[60:63], v[184:187], v[164:167], v[60:63]
	v_mfma_f32_16x16x32_bf16 v[56:59], v[184:187], v[172:175], v[56:59]
	v_mfma_f32_16x16x32_bf16 v[52:55], v[194:197], v[164:167], v[52:55]
	v_mfma_f32_16x16x32_bf16 v[48:51], v[194:197], v[172:175], v[48:51]
	v_mfma_f32_16x16x32_bf16 v[44:47], v[206:209], v[164:167], v[44:47]
	v_mfma_f32_16x16x32_bf16 v[40:43], v[206:209], v[172:175], v[40:43]
	v_mfma_f32_16x16x32_bf16 v[36:39], v[216:219], v[164:167], v[36:39]
	v_mfma_f32_16x16x32_bf16 v[32:35], v[216:219], v[172:175], v[32:35]
	v_mfma_f32_16x16x32_bf16 v[60:63], v[190:193], v[168:171], v[60:63]
	v_mfma_f32_16x16x32_bf16 v[56:59], v[190:193], v[176:179], v[56:59]
	v_mfma_f32_16x16x32_bf16 v[52:55], v[198:201], v[168:171], v[52:55]
	v_mfma_f32_16x16x32_bf16 v[48:51], v[198:201], v[176:179], v[48:51]
	v_mfma_f32_16x16x32_bf16 v[44:47], v[212:215], v[168:171], v[44:47]
	v_mfma_f32_16x16x32_bf16 v[40:43], v[212:215], v[176:179], v[40:43]
	v_mfma_f32_16x16x32_bf16 v[36:39], v[220:223], v[168:171], v[36:39]
	v_mfma_f32_16x16x32_bf16 v[32:35], v[220:223], v[176:179], v[32:35]
	s_setprio 0
	s_barrier
	s_add_i32 m0, s101, 0x1be80
	s_nop 0
	global_load_lds_dwordx4 v[252:253], off offset:384
	s_add_i32 m0, m0, 0x2000
	s_nop 0
	global_load_lds_dwordx4 v[188:189], off offset:384
	s_waitcnt vmcnt(6)
	s_barrier
	s_setprio 1
	v_mfma_f32_16x16x32_bf16 v[28:31], v[184:187], v[224:227], v[28:31]
	v_mfma_f32_16x16x32_bf16 v[24:27], v[184:187], v[232:235], v[24:27]
	v_mfma_f32_16x16x32_bf16 v[20:23], v[194:197], v[224:227], v[20:23]
	v_mfma_f32_16x16x32_bf16 v[16:19], v[194:197], v[232:235], v[16:19]
	v_mfma_f32_16x16x32_bf16 v[12:15], v[206:209], v[224:227], v[12:15]
	v_mfma_f32_16x16x32_bf16 v[8:11], v[206:209], v[232:235], v[8:11]
	v_mfma_f32_16x16x32_bf16 v[4:7], v[216:219], v[224:227], v[4:7]
	v_mfma_f32_16x16x32_bf16 v[0:3], v[216:219], v[232:235], v[0:3]
	v_mfma_f32_16x16x32_bf16 v[28:31], v[190:193], v[228:231], v[28:31]
	v_mfma_f32_16x16x32_bf16 v[24:27], v[190:193], v[236:239], v[24:27]
	v_mfma_f32_16x16x32_bf16 v[20:23], v[198:201], v[228:231], v[20:23]
	v_mfma_f32_16x16x32_bf16 v[16:19], v[198:201], v[236:239], v[16:19]
	v_mfma_f32_16x16x32_bf16 v[12:15], v[212:215], v[228:231], v[12:15]
	v_mfma_f32_16x16x32_bf16 v[8:11], v[212:215], v[236:239], v[8:11]
	v_mfma_f32_16x16x32_bf16 v[4:7], v[220:223], v[228:231], v[4:7]
	v_mfma_f32_16x16x32_bf16 v[0:3], v[220:223], v[236:239], v[0:3]
	s_setprio 0
	s_add_u32 s6, s6, 0x100
	s_addc_u32 s7, s7, 0
	s_cmp_lt_u32 s11, s10
	s_barrier
	s_cbranch_scc1 .LBB0_219
	v_add_u32_e32 v161, 0xc000, v148
	v_add_u32_e32 v162, 0xe000, v148
	s_or_b32 s6, s60, 0x80
	s_mul_hi_u32 s7, s6, s15
	s_mul_i32 s10, s61, s15
	s_add_i32 s7, s7, s10
	s_mul_i32 s6, s6, s15
	s_lshl_b64 s[6:7], s[6:7], 1
	s_add_u32 s6, s4, s6
	s_addc_u32 s7, s5, s7
	s_add_i32 s36, s12, -1
	s_lshl_b64 s[4:5], s[36:37], 7
	s_add_u32 s4, s6, s4
	s_addc_u32 s5, s7, s5
	v_readfirstlane_b32 s6, v161
	v_lshl_add_u64 v[156:157], v[180:181], 1, s[4:5]
	s_mov_b32 m0, s6
	v_lshl_add_u64 v[128:129], v[128:129], 1, s[4:5]
	v_readfirstlane_b32 s4, v162
	ds_read_b128 v[130:133], v160
	ds_read_b128 v[134:137], v160 offset:1024
	ds_read_b128 v[138:141], v160 offset:2048
	ds_read_b128 v[142:145], v160 offset:3072
	ds_read_b128 v[164:167], v152
	ds_read_b128 v[168:171], v152 offset:1024
	ds_read_b128 v[172:175], v151
	ds_read_b128 v[176:179], v151 offset:1024
	ds_read_b128 v[184:187], v150
	ds_read_b128 v[190:193], v150 offset:1024
	ds_read_b128 v[194:197], v149
	ds_read_b128 v[198:201], v149 offset:1024
	global_load_lds_dwordx4 v[156:157], off
	s_mov_b32 m0, s4
	s_nop 0
	global_load_lds_dwordx4 v[128:129], off
	s_barrier
	s_waitcnt lgkmcnt(0)
	s_setprio 1
	s_waitcnt lgkmcnt(0)
	v_mfma_f32_16x16x32_bf16 v[124:127], v[164:167], v[130:133], v[124:127]
	v_mfma_f32_16x16x32_bf16 v[116:119], v[172:175], v[130:133], v[116:119]
	v_mfma_f32_16x16x32_bf16 v[108:111], v[184:187], v[130:133], v[108:111]
	v_mfma_f32_16x16x32_bf16 v[100:103], v[194:197], v[130:133], v[100:103]
	v_mfma_f32_16x16x32_bf16 v[124:127], v[168:171], v[134:137], v[124:127]
	v_mfma_f32_16x16x32_bf16 v[120:123], v[164:167], v[138:141], v[120:123]
	v_mfma_f32_16x16x32_bf16 v[116:119], v[176:179], v[134:137], v[116:119]
	v_mfma_f32_16x16x32_bf16 v[112:115], v[172:175], v[138:141], v[112:115]
	v_mfma_f32_16x16x32_bf16 v[108:111], v[190:193], v[134:137], v[108:111]
	v_mfma_f32_16x16x32_bf16 v[104:107], v[184:187], v[138:141], v[104:107]
	v_mfma_f32_16x16x32_bf16 v[100:103], v[198:201], v[134:137], v[100:103]
	v_mfma_f32_16x16x32_bf16 v[96:99], v[194:197], v[138:141], v[96:99]
	v_mfma_f32_16x16x32_bf16 v[160:163], v[168:171], v[142:145], v[120:123]
	v_mfma_f32_16x16x32_bf16 v[206:209], v[176:179], v[142:145], v[112:115]
	v_mfma_f32_16x16x32_bf16 v[212:215], v[190:193], v[142:145], v[104:107]
	v_mfma_f32_16x16x32_bf16 v[216:219], v[198:201], v[142:145], v[96:99]
	s_setprio 0
	s_barrier
	s_nop 1
	ds_read_b128 v[96:99], v159
	ds_read_b128 v[104:107], v159 offset:1024
	ds_read_b128 v[112:115], v159 offset:2048
	ds_read_b128 v[120:123], v159 offset:3072
	s_barrier
	s_waitcnt lgkmcnt(0)
	s_setprio 1
	s_waitcnt lgkmcnt(0)
	v_mfma_f32_16x16x32_bf16 v[92:95], v[164:167], v[96:99], v[92:95]
	v_mfma_f32_16x16x32_bf16 v[84:87], v[172:175], v[96:99], v[84:87]
	v_mfma_f32_16x16x32_bf16 v[76:79], v[184:187], v[96:99], v[76:79]
	v_mfma_f32_16x16x32_bf16 v[68:71], v[194:197], v[96:99], v[68:71]
	v_mfma_f32_16x16x32_bf16 v[92:95], v[168:171], v[104:107], v[92:95]
	v_mfma_f32_16x16x32_bf16 v[88:91], v[164:167], v[112:115], v[88:91]
	v_mfma_f32_16x16x32_bf16 v[84:87], v[176:179], v[104:107], v[84:87]
	v_mfma_f32_16x16x32_bf16 v[80:83], v[172:175], v[112:115], v[80:83]
	v_mfma_f32_16x16x32_bf16 v[76:79], v[190:193], v[104:107], v[76:79]
	v_mfma_f32_16x16x32_bf16 v[72:75], v[184:187], v[112:115], v[72:75]
	v_mfma_f32_16x16x32_bf16 v[68:71], v[198:201], v[104:107], v[68:71]
	v_mfma_f32_16x16x32_bf16 v[64:67], v[194:197], v[112:115], v[64:67]
	v_mfma_f32_16x16x32_bf16 v[156:159], v[168:171], v[120:123], v[88:91]
	v_mfma_f32_16x16x32_bf16 v[164:167], v[176:179], v[120:123], v[80:83]
	v_mfma_f32_16x16x32_bf16 v[168:171], v[190:193], v[120:123], v[72:75]
	v_mfma_f32_16x16x32_bf16 v[172:175], v[198:201], v[120:123], v[64:67]
	s_setprio 0
	s_barrier
	s_nop 1
	ds_read_b128 v[64:67], v152 offset:16384
	ds_read_b128 v[72:75], v152 offset:17408
	ds_read_b128 v[80:83], v151 offset:16384
	ds_read_b128 v[88:91], v151 offset:17408
	ds_read_b128 v[176:179], v150 offset:16384
	ds_read_b128 v[184:187], v150 offset:17408
	ds_read_b128 v[190:193], v149 offset:16384
	ds_read_b128 v[194:197], v149 offset:17408
	s_waitcnt vmcnt(4)
	s_barrier
	s_waitcnt lgkmcnt(0)
	s_setprio 1
	s_waitcnt lgkmcnt(0)
	v_mfma_f32_16x16x32_bf16 v[60:63], v[64:67], v[130:133], v[60:63]
	v_mfma_f32_16x16x32_bf16 v[52:55], v[80:83], v[130:133], v[52:55]
	v_mfma_f32_16x16x32_bf16 v[44:47], v[176:179], v[130:133], v[44:47]
	v_mfma_f32_16x16x32_bf16 v[36:39], v[190:193], v[130:133], v[36:39]
	v_mfma_f32_16x16x32_bf16 v[60:63], v[72:75], v[134:137], v[60:63]
	v_mfma_f32_16x16x32_bf16 v[56:59], v[64:67], v[138:141], v[56:59]
	v_mfma_f32_16x16x32_bf16 v[52:55], v[88:91], v[134:137], v[52:55]
	v_mfma_f32_16x16x32_bf16 v[48:51], v[80:83], v[138:141], v[48:51]
	v_mfma_f32_16x16x32_bf16 v[44:47], v[184:187], v[134:137], v[44:47]
	v_mfma_f32_16x16x32_bf16 v[40:43], v[176:179], v[138:141], v[40:43]
	v_mfma_f32_16x16x32_bf16 v[36:39], v[194:197], v[134:137], v[36:39]
	v_mfma_f32_16x16x32_bf16 v[32:35], v[190:193], v[138:141], v[32:35]
	v_mfma_f32_16x16x32_bf16 v[198:201], v[72:75], v[142:145], v[56:59]
	v_mfma_f32_16x16x32_bf16 v[220:223], v[88:91], v[142:145], v[48:51]
	v_mfma_f32_16x16x32_bf16 v[224:227], v[184:187], v[142:145], v[40:43]
	v_mfma_f32_16x16x32_bf16 v[128:131], v[194:197], v[142:145], v[32:35]
	s_setprio 0
	s_setprio 1
	v_mfma_f32_16x16x32_bf16 v[28:31], v[64:67], v[96:99], v[28:31]
	v_mfma_f32_16x16x32_bf16 v[20:23], v[80:83], v[96:99], v[20:23]
	v_mfma_f32_16x16x32_bf16 v[12:15], v[176:179], v[96:99], v[12:15]
	v_mfma_f32_16x16x32_bf16 v[4:7], v[190:193], v[96:99], v[4:7]
	v_mfma_f32_16x16x32_bf16 v[28:31], v[72:75], v[104:107], v[28:31]
	v_mfma_f32_16x16x32_bf16 v[24:27], v[64:67], v[112:115], v[24:27]
	v_mfma_f32_16x16x32_bf16 v[20:23], v[88:91], v[104:107], v[20:23]
	v_mfma_f32_16x16x32_bf16 v[16:19], v[80:83], v[112:115], v[16:19]
	v_mfma_f32_16x16x32_bf16 v[12:15], v[184:187], v[104:107], v[12:15]
	v_mfma_f32_16x16x32_bf16 v[8:11], v[176:179], v[112:115], v[8:11]
	v_mfma_f32_16x16x32_bf16 v[4:7], v[194:197], v[104:107], v[4:7]
	v_mfma_f32_16x16x32_bf16 v[0:3], v[190:193], v[112:115], v[0:3]
	v_mfma_f32_16x16x32_bf16 v[132:135], v[72:75], v[120:123], v[24:27]
	v_mfma_f32_16x16x32_bf16 v[136:139], v[88:91], v[120:123], v[16:19]
	v_mfma_f32_16x16x32_bf16 v[140:143], v[184:187], v[120:123], v[8:11]
	v_mfma_f32_16x16x32_bf16 v[176:179], v[194:197], v[120:123], v[0:3]
	s_setprio 0
	s_barrier
	s_nop 1
	ds_read_b128 v[0:3], v155
	ds_read_b128 v[8:11], v155 offset:1024
	ds_read_b128 v[16:19], v155 offset:2048
	ds_read_b128 v[24:27], v155 offset:3072
	ds_read_b128 v[32:35], v152 offset:32768
	ds_read_b128 v[40:43], v152 offset:33792
	ds_read_b128 v[48:51], v151 offset:32768
	ds_read_b128 v[56:59], v151 offset:33792
	ds_read_b128 v[64:67], v150 offset:32768
	ds_read_b128 v[184:187], v150 offset:33792
	ds_read_b128 v[190:193], v149 offset:32768
	ds_read_b128 v[194:197], v149 offset:33792
	s_waitcnt vmcnt(2)
	s_barrier
	s_waitcnt lgkmcnt(0)
	s_setprio 1
	s_waitcnt lgkmcnt(0)
	v_mfma_f32_16x16x32_bf16 v[72:75], v[32:35], v[0:3], v[124:127]
	v_mfma_f32_16x16x32_bf16 v[120:123], v[40:43], v[8:11], v[72:75]
	v_mfma_f32_16x16x32_bf16 v[72:75], v[32:35], v[16:19], v[160:163]
	v_mfma_f32_16x16x32_bf16 v[124:127], v[40:43], v[24:27], v[72:75]
	v_mfma_f32_16x16x32_bf16 v[72:75], v[48:51], v[0:3], v[116:119]
	v_mfma_f32_16x16x32_bf16 v[112:115], v[56:59], v[8:11], v[72:75]
	v_mfma_f32_16x16x32_bf16 v[72:75], v[48:51], v[16:19], v[206:209]
	v_mfma_f32_16x16x32_bf16 v[116:119], v[56:59], v[24:27], v[72:75]
	v_mfma_f32_16x16x32_bf16 v[72:75], v[64:67], v[0:3], v[108:111]
	v_mfma_f32_16x16x32_bf16 v[104:107], v[184:187], v[8:11], v[72:75]
	v_mfma_f32_16x16x32_bf16 v[72:75], v[64:67], v[16:19], v[212:215]
	v_mfma_f32_16x16x32_bf16 v[108:111], v[184:187], v[24:27], v[72:75]
	v_mfma_f32_16x16x32_bf16 v[72:75], v[190:193], v[0:3], v[100:103]
	v_mfma_f32_16x16x32_bf16 v[96:99], v[194:197], v[8:11], v[72:75]
	v_mfma_f32_16x16x32_bf16 v[72:75], v[190:193], v[16:19], v[216:219]
	v_mfma_f32_16x16x32_bf16 v[100:103], v[194:197], v[24:27], v[72:75]
	s_setprio 0
	s_barrier
	ds_read_b128 v[160:163], v153
	ds_read_b128 v[206:209], v153 offset:1024
	ds_read_b128 v[212:215], v153 offset:2048
	ds_read_b128 v[216:219], v153 offset:3072
	s_waitcnt vmcnt(0)
	s_barrier
	s_waitcnt lgkmcnt(0)
	s_setprio 1
	s_waitcnt lgkmcnt(0)
	v_mfma_f32_16x16x32_bf16 v[72:75], v[32:35], v[160:163], v[92:95]
	v_mfma_f32_16x16x32_bf16 v[32:35], v[32:35], v[212:215], v[156:159]
	v_mfma_f32_16x16x32_bf16 v[92:95], v[40:43], v[216:219], v[32:35]
	v_mfma_f32_16x16x32_bf16 v[32:35], v[48:51], v[160:163], v[84:87]
	v_mfma_f32_16x16x32_bf16 v[80:83], v[56:59], v[206:209], v[32:35]
	v_mfma_f32_16x16x32_bf16 v[32:35], v[48:51], v[212:215], v[164:167]
	v_mfma_f32_16x16x32_bf16 v[84:87], v[56:59], v[216:219], v[32:35]
	v_mfma_f32_16x16x32_bf16 v[32:35], v[64:67], v[160:163], v[76:79]
	v_mfma_f32_16x16x32_bf16 v[88:91], v[40:43], v[206:209], v[72:75]
	v_mfma_f32_16x16x32_bf16 v[72:75], v[184:187], v[206:209], v[32:35]
	v_mfma_f32_16x16x32_bf16 v[32:35], v[64:67], v[212:215], v[168:171]
	v_mfma_f32_16x16x32_bf16 v[76:79], v[184:187], v[216:219], v[32:35]
	v_mfma_f32_16x16x32_bf16 v[32:35], v[190:193], v[160:163], v[68:71]
	v_mfma_f32_16x16x32_bf16 v[64:67], v[194:197], v[206:209], v[32:35]
	v_mfma_f32_16x16x32_bf16 v[32:35], v[190:193], v[212:215], v[172:175]
	v_mfma_f32_16x16x32_bf16 v[68:71], v[194:197], v[216:219], v[32:35]
	s_setprio 0
	s_barrier
	ds_read_b128 v[154:157], v152 offset:49152
	ds_read_b128 v[164:167], v152 offset:50176
	ds_read_b128 v[168:171], v151 offset:49152
	ds_read_b128 v[172:175], v151 offset:50176
	ds_read_b128 v[184:187], v150 offset:49152
	ds_read_b128 v[150:153], v150 offset:50176
	ds_read_b128 v[190:193], v149 offset:49152
	ds_read_b128 v[194:197], v149 offset:50176
	s_barrier
	s_waitcnt lgkmcnt(0)
	s_setprio 1
	s_waitcnt lgkmcnt(0)
	v_mfma_f32_16x16x32_bf16 v[32:35], v[154:157], v[0:3], v[60:63]
	v_mfma_f32_16x16x32_bf16 v[56:59], v[164:167], v[8:11], v[32:35]
	v_mfma_f32_16x16x32_bf16 v[32:35], v[154:157], v[16:19], v[198:201]
	v_mfma_f32_16x16x32_bf16 v[60:63], v[164:167], v[24:27], v[32:35]
	v_mfma_f32_16x16x32_bf16 v[32:35], v[168:171], v[0:3], v[52:55]
	v_mfma_f32_16x16x32_bf16 v[48:51], v[172:175], v[8:11], v[32:35]
	v_mfma_f32_16x16x32_bf16 v[32:35], v[168:171], v[16:19], v[220:223]
	v_mfma_f32_16x16x32_bf16 v[52:55], v[172:175], v[24:27], v[32:35]
	v_mfma_f32_16x16x32_bf16 v[32:35], v[184:187], v[0:3], v[44:47]
	v_mfma_f32_16x16x32_bf16 v[40:43], v[150:153], v[8:11], v[32:35]
	v_mfma_f32_16x16x32_bf16 v[32:35], v[184:187], v[16:19], v[224:227]
	v_mfma_f32_16x16x32_bf16 v[0:3], v[190:193], v[0:3], v[36:39]
	v_mfma_f32_16x16x32_bf16 v[44:47], v[150:153], v[24:27], v[32:35]
	v_mfma_f32_16x16x32_bf16 v[32:35], v[194:197], v[8:11], v[0:3]
	v_mfma_f32_16x16x32_bf16 v[0:3], v[190:193], v[16:19], v[128:131]
	v_mfma_f32_16x16x32_bf16 v[36:39], v[194:197], v[24:27], v[0:3]
	s_setprio 0
	s_setprio 1
	v_mfma_f32_16x16x32_bf16 v[0:3], v[154:157], v[160:163], v[28:31]
	v_mfma_f32_16x16x32_bf16 v[24:27], v[164:167], v[206:209], v[0:3]
	v_mfma_f32_16x16x32_bf16 v[0:3], v[154:157], v[212:215], v[132:135]
	v_mfma_f32_16x16x32_bf16 v[28:31], v[164:167], v[216:219], v[0:3]
	v_mfma_f32_16x16x32_bf16 v[0:3], v[168:171], v[160:163], v[20:23]
	v_mfma_f32_16x16x32_bf16 v[16:19], v[172:175], v[206:209], v[0:3]
	v_mfma_f32_16x16x32_bf16 v[0:3], v[168:171], v[212:215], v[136:139]
	v_mfma_f32_16x16x32_bf16 v[20:23], v[172:175], v[216:219], v[0:3]
	v_mfma_f32_16x16x32_bf16 v[0:3], v[184:187], v[160:163], v[12:15]
	v_mfma_f32_16x16x32_bf16 v[8:11], v[150:153], v[206:209], v[0:3]
	v_mfma_f32_16x16x32_bf16 v[0:3], v[184:187], v[212:215], v[140:143]
	v_mfma_f32_16x16x32_bf16 v[12:15], v[150:153], v[216:219], v[0:3]
	v_mfma_f32_16x16x32_bf16 v[0:3], v[190:193], v[160:163], v[4:7]
	v_mfma_f32_16x16x32_bf16 v[4:7], v[190:193], v[212:215], v[176:179]
	v_mfma_f32_16x16x32_bf16 v[0:3], v[194:197], v[206:209], v[0:3]
	v_mfma_f32_16x16x32_bf16 v[4:7], v[194:197], v[216:219], v[4:7]
	s_setprio 0
	s_movk_i32 s4, 0x100
	v_cmp_gt_u32_e32 vcc, s4, v146
	s_barrier
	s_and_saveexec_b64 s[4:5], vcc
	s_cbranch_execz .LBB0_222
	s_barrier
